# P1 epilogue: hand-written path also for the u=cc*ch tiles (pn 1,2) of panels without conv-state output rows
# speedup vs baseline: 1.0090x; 1.0090x over previous
; DI v4u pack8(f32x4 a, f32x4 b) { v4u w; w.x = cvtpk(a[0], a[1]); w.y = cvtpk(a[2], a[3]); w.z = cvtpk(b[0], b[1]); w.w = cvtpk(b[2], b[3]); return w; }
;     DI void operator()(const f32x4 (&acc)[2][2][4][2], const pg8::Unit& u, int wr, int wc, int fr, int fq) const {
;         const int pn = u.pn, rb = u.pm * 256 + wr * 64 + fr, cl = wc * 32 + 8 * fq;
;         if (pn == 1 || pn == 2) {
;             const int col = (pn - 1) * 128 + cl;
; #pragma unroll
;             for (int ai = 0; ai < 2; ++ai)
; #pragma unroll
;                 for (int m = 0; m < 4; ++m) { const int row = rb + ai * 128 + m * 16;
;                     const f32x4 a0 = acc[ai][0][m][0] * acc[ai][1][m][0], a1 = acc[ai][0][m][1] * acc[ai][1][m][1];
;                     *(v4u*)(U + (size_t)row * 256 + col) = pack8(a0, a1);
.Lep_u_chk:
	s_cmp_gt_u32 s0, 63
	s_cbranch_scc1 .Lep_orig
	s_and_b32 s12, s0, 31
	s_cmp_eq_u32 s12, 31
	s_cbranch_scc1 .Lep_orig
	v_and_b32_e32 v150, 15, v0
	v_bfe_u32 v151, v0, 4, 2
	v_bfe_u32 v152, v0, 6, 2
	v_lshrrev_b32_e32 v153, 8, v0
	v_lshl_add_u32 v150, v153, 6, v150
	v_lshlrev_b32_e32 v151, 3, v151
	v_lshl_add_u32 v151, v152, 5, v151
	s_lshl_b32 s1, s0, 8
	v_readlane_b32 s4, v247, 45
	v_readlane_b32 s5, v247, 46
	s_mov_b32 s18, 8
	s_sub_u32 s19, s90, 1
	s_lshl_b32 s19, s19, 7
	s_mov_b32 s3, 4
	s_add_u32 s4, s4, 0xa00000
	s_addc_u32 s5, s5, 0
	s_branch .Lep_addr

; DI v4u pack8(f32x4 a, f32x4 b) { v4u w; w.x = cvtpk(a[0], a[1]); w.y = cvtpk(a[2], a[3]); w.z = cvtpk(b[0], b[1]); w.w = cvtpk(b[2], b[3]); return w; }
; DI float silu_f(float z) { return z * __builtin_amdgcn_rcpf(1.f + fexp2(-z * LOG2E)); }
;     DI void operator()(const f32x4 (&acc)[2][2][4][2], const pg8::Unit& u, int wr, int wc, int fr, int fq) const {
;     ...
;         bf16* dst; int ld, c0; float sc = 1.f; int kind = 0;
;         size_t o_p = 0, o_s = 0;
;         if (pn == 0) { dst = CB; ld = 256; c0 = 0; }
;         else if (pn <= 4) { dst = Q; ld = 512; c0 = (pn - 3) * 256; sc = QSCALE; }
;         else if (pn <= 6) { dst = K; ld = 512; c0 = (pn - 5) * 256; kind = 1; o_p = O_PWK; o_s = O_SWK; }
;         else if (pn <= 8) { dst = V; ld = 512; c0 = (pn - 7) * 256; kind = 1; o_p = O_PWV; o_s = O_SWV; }
;         else if (pn == 9) { dst = MQ; ld = 256; c0 = 0; sc = QSCALE; }
;         else if (pn <= 13) { dst = G; ld = 1024; c0 = (pn - 10) * 256; kind = 2; }
;         else { dst = (pn == 14) ? MK : MV; ld = 256; c0 = 0; kind = 3; o_p = (pn == 14) ? O_PMK : O_PMV; }
; #pragma unroll
;         for (int ai = 0; ai < 2; ++ai)
; #pragma unroll
;             for (int m = 0; m < 4; ++m) { const int row = rb + ai * 128 + m * 16;
; #pragma unroll
;                 for (int bj = 0; bj < 2; ++bj) { const int col = c0 + bj * 128 + cl;
;                     f32x4 v0 = acc[ai][bj][m][0], v1 = acc[ai][bj][m][1];
;                     if (kind == 3) { const int mr = row - MT;
;                         *(v4u*)(dst + (size_t)mr * ld + col) = pack8(v0, v1);
;                         float* fo = out + o_p + (size_t)mr * 256 + col; *(f32x4*)fo = v0; *(f32x4*)(fo + 4) = v1; continue; }
;                     if (kind == 1) { float* fo = nullptr;
;                         if (row < MP) { const int t = row & (SEQ - 1); if (t >= SEQ - 2048) fo = out + o_p + ((size_t)((row >> 13) * 2048 + (t - (SEQ - 2048)))) * 512 + col; }
;                         else fo = out + o_s + (size_t)(row - MP) * 512 + col;
;                         if (fo) { *(f32x4*)fo = v0; *(f32x4*)(fo + 4) = v1; } }
;                     if (kind == 2) {
; #pragma unroll
;                         for (int e = 0; e < 4; ++e) { v0[e] = silu_f(v0[e]); v1[e] = silu_f(v1[e]); } }
;                     else { v0 = v0 * sc; v1 = v1 * sc; }
;                     *(v4u*)(dst + (size_t)row * ld + col) = pack8(v0, v1); } }
.Lep_addr:
	s_lshl_b32 s1, s1, s18
	s_add_u32 s1, s1, s19
	s_lshl_b32 s1, s1, 1
	s_add_u32 s4, s4, s1
	s_addc_u32 s5, s5, 0
	v_lshlrev_b32_e32 v152, s18, v150
	v_add_lshl_u32 v152, v152, v151, 1
	s_lshl_b32 s92, 32, s18
	s_lshl_b32 s93, 0x100, s18
	v_mov_b32_e32 v153, v152
	s_cmp_eq_u32 s3, 4
	s_cbranch_scc1 .Lep_u
	s_cmp_eq_u32 s3, 1
	s_cbranch_scc1 .Lep_scale
	s_cmp_eq_u32 s3, 2
	s_cbranch_scc1 .Lep_silu
	s_cmp_eq_u32 s3, 3
	s_cbranch_scc1 .Lep_plainf
	v_cvt_pk_bf16_f32 v130, v126, v127
	v_cvt_pk_bf16_f32 v131, v128, v129
	v_cvt_pk_bf16_f32 v132, v122, v123
	v_cvt_pk_bf16_f32 v133, v124, v125
	global_store_dwordx4 v153, v[130:133], s[4:5]
	v_cvt_pk_bf16_f32 v154, v118, v119
	v_cvt_pk_bf16_f32 v155, v120, v121
	v_cvt_pk_bf16_f32 v156, v114, v115
	v_cvt_pk_bf16_f32 v157, v116, v117
	global_store_dwordx4 v153, v[154:157], s[4:5] offset:256
	v_add_u32_e32 v153, s92, v153
	v_cvt_pk_bf16_f32 v130, v110, v111
	v_cvt_pk_bf16_f32 v131, v112, v113
	v_cvt_pk_bf16_f32 v132, v106, v107
	v_cvt_pk_bf16_f32 v133, v108, v109
	global_store_dwordx4 v153, v[130:133], s[4:5]
	v_cvt_pk_bf16_f32 v154, v102, v103
	v_cvt_pk_bf16_f32 v155, v104, v105
	v_cvt_pk_bf16_f32 v156, v98, v99
	v_cvt_pk_bf16_f32 v157, v100, v101
	global_store_dwordx4 v153, v[154:157], s[4:5] offset:256
	v_add_u32_e32 v153, s92, v153
	v_cvt_pk_bf16_f32 v130, v94, v95
	v_cvt_pk_bf16_f32 v131, v96, v97
	v_cvt_pk_bf16_f32 v132, v90, v91
	v_cvt_pk_bf16_f32 v133, v92, v93
	global_store_dwordx4 v153, v[130:133], s[4:5]
	v_cvt_pk_bf16_f32 v154, v86, v87
	v_cvt_pk_bf16_f32 v155, v88, v89
	v_cvt_pk_bf16_f32 v156, v82, v83
	v_cvt_pk_bf16_f32 v157, v84, v85
	global_store_dwordx4 v153, v[154:157], s[4:5] offset:256
	v_add_u32_e32 v153, s92, v153
	v_cvt_pk_bf16_f32 v130, v78, v79
	v_cvt_pk_bf16_f32 v131, v80, v81
	v_cvt_pk_bf16_f32 v132, v74, v75
	v_cvt_pk_bf16_f32 v133, v76, v77
	global_store_dwordx4 v153, v[130:133], s[4:5]
	v_cvt_pk_bf16_f32 v154, v70, v71
	v_cvt_pk_bf16_f32 v155, v72, v73
	v_cvt_pk_bf16_f32 v156, v66, v67
	v_cvt_pk_bf16_f32 v157, v68, v69
	global_store_dwordx4 v153, v[154:157], s[4:5] offset:256
	v_add_u32_e32 v153, s93, v152
	v_cvt_pk_bf16_f32 v130, v62, v63
	v_cvt_pk_bf16_f32 v131, v64, v65
	v_cvt_pk_bf16_f32 v132, v58, v59
	v_cvt_pk_bf16_f32 v133, v60, v61
	global_store_dwordx4 v153, v[130:133], s[4:5]
	v_cvt_pk_bf16_f32 v154, v54, v55
	v_cvt_pk_bf16_f32 v155, v56, v57
	v_cvt_pk_bf16_f32 v156, v50, v51
	v_cvt_pk_bf16_f32 v157, v52, v53
	global_store_dwordx4 v153, v[154:157], s[4:5] offset:256
	v_add_u32_e32 v153, s92, v153
	v_cvt_pk_bf16_f32 v130, v46, v47
	v_cvt_pk_bf16_f32 v131, v48, v49
	v_cvt_pk_bf16_f32 v132, v42, v43
	v_cvt_pk_bf16_f32 v133, v44, v45
	global_store_dwordx4 v153, v[130:133], s[4:5]
	v_cvt_pk_bf16_f32 v154, v38, v39
	v_cvt_pk_bf16_f32 v155, v40, v41
	v_cvt_pk_bf16_f32 v156, v34, v35
	v_cvt_pk_bf16_f32 v157, v36, v37
	global_store_dwordx4 v153, v[154:157], s[4:5] offset:256
	v_add_u32_e32 v153, s92, v153
	v_cvt_pk_bf16_f32 v130, v30, v31
	v_cvt_pk_bf16_f32 v131, v32, v33
	v_cvt_pk_bf16_f32 v132, v26, v27
	v_cvt_pk_bf16_f32 v133, v28, v29
	global_store_dwordx4 v153, v[130:133], s[4:5]
	v_cvt_pk_bf16_f32 v154, v22, v23
	v_cvt_pk_bf16_f32 v155, v24, v25
	v_cvt_pk_bf16_f32 v156, v18, v19
	v_cvt_pk_bf16_f32 v157, v20, v21
	global_store_dwordx4 v153, v[154:157], s[4:5] offset:256
	v_add_u32_e32 v153, s92, v153
	v_cvt_pk_bf16_f32 v130, v14, v15
	v_cvt_pk_bf16_f32 v131, v16, v17
	v_cvt_pk_bf16_f32 v132, v10, v11
	v_cvt_pk_bf16_f32 v133, v12, v13
	global_store_dwordx4 v153, v[130:133], s[4:5]
	v_cvt_pk_bf16_f32 v154, v6, v7
	v_cvt_pk_bf16_f32 v155, v8, v9
	v_cvt_pk_bf16_f32 v156, v2, v3
	v_cvt_pk_bf16_f32 v157, v4, v5
	global_store_dwordx4 v153, v[154:157], s[4:5] offset:256
	s_branch .LBB0_374

; DI v4u pack8(f32x4 a, f32x4 b) { v4u w; w.x = cvtpk(a[0], a[1]); w.y = cvtpk(a[2], a[3]); w.z = cvtpk(b[0], b[1]); w.w = cvtpk(b[2], b[3]); return w; }
;     DI void operator()(const f32x4 (&acc)[2][2][4][2], const pg8::Unit& u, int wr, int wc, int fr, int fq) const {
;     ...
;         if (pn == 1 || pn == 2) {
;             const int col = (pn - 1) * 128 + cl;
; #pragma unroll
;             for (int ai = 0; ai < 2; ++ai)
; #pragma unroll
;                 for (int m = 0; m < 4; ++m) { const int row = rb + ai * 128 + m * 16;
;                     const f32x4 a0 = acc[ai][0][m][0] * acc[ai][1][m][0], a1 = acc[ai][0][m][1] * acc[ai][1][m][1];
;                     *(v4u*)(U + (size_t)row * 256 + col) = pack8(a0, a1);
;                     float* fo = nullptr;
;                     if (row < MP) { const int t = row & (SEQ - 1); if (t >= SEQ - 2) fo = out + O_PCV + ((size_t)((row >> 13) * 2 + (t - (SEQ - 2)))) * 256 + col; }
;                     else { const int sr = row - MP, j = sr & 3; if (j >= 2) fo = out + O_SCV + ((size_t)((sr >> 2) * 2 + (j - 2))) * 256 + col; }
;                     if (fo) { *(f32x4*)fo = a0; *(f32x4*)(fo + 4) = a1; } }
;             return;
.Lep_u:
	v_pk_mul_f32 v[154:155], v[126:127], v[118:119]
	v_pk_mul_f32 v[156:157], v[128:129], v[120:121]
	v_pk_mul_f32 v[158:159], v[122:123], v[114:115]
	v_pk_mul_f32 v[160:161], v[124:125], v[116:117]
	v_cvt_pk_bf16_f32 v130, v154, v155
	v_cvt_pk_bf16_f32 v131, v156, v157
	v_cvt_pk_bf16_f32 v132, v158, v159
	v_cvt_pk_bf16_f32 v133, v160, v161
	global_store_dwordx4 v153, v[130:133], s[4:5]
	v_add_u32_e32 v153, s92, v153
	v_pk_mul_f32 v[154:155], v[110:111], v[102:103]
	v_pk_mul_f32 v[156:157], v[112:113], v[104:105]
	v_pk_mul_f32 v[158:159], v[106:107], v[98:99]
	v_pk_mul_f32 v[160:161], v[108:109], v[100:101]
	v_cvt_pk_bf16_f32 v130, v154, v155
	v_cvt_pk_bf16_f32 v131, v156, v157
	v_cvt_pk_bf16_f32 v132, v158, v159
	v_cvt_pk_bf16_f32 v133, v160, v161
	global_store_dwordx4 v153, v[130:133], s[4:5]
	v_add_u32_e32 v153, s92, v153
	v_pk_mul_f32 v[154:155], v[94:95], v[86:87]
	v_pk_mul_f32 v[156:157], v[96:97], v[88:89]
	v_pk_mul_f32 v[158:159], v[90:91], v[82:83]
	v_pk_mul_f32 v[160:161], v[92:93], v[84:85]
	v_cvt_pk_bf16_f32 v130, v154, v155
	v_cvt_pk_bf16_f32 v131, v156, v157
	v_cvt_pk_bf16_f32 v132, v158, v159
	v_cvt_pk_bf16_f32 v133, v160, v161
	global_store_dwordx4 v153, v[130:133], s[4:5]
	v_add_u32_e32 v153, s92, v153
	v_pk_mul_f32 v[154:155], v[78:79], v[70:71]
	v_pk_mul_f32 v[156:157], v[80:81], v[72:73]
	v_pk_mul_f32 v[158:159], v[74:75], v[66:67]
	v_pk_mul_f32 v[160:161], v[76:77], v[68:69]
	v_cvt_pk_bf16_f32 v130, v154, v155
	v_cvt_pk_bf16_f32 v131, v156, v157
	v_cvt_pk_bf16_f32 v132, v158, v159
	v_cvt_pk_bf16_f32 v133, v160, v161
	global_store_dwordx4 v153, v[130:133], s[4:5]
	v_add_u32_e32 v153, s93, v152
	v_pk_mul_f32 v[154:155], v[62:63], v[54:55]
	v_pk_mul_f32 v[156:157], v[64:65], v[56:57]
	v_pk_mul_f32 v[158:159], v[58:59], v[50:51]
	v_pk_mul_f32 v[160:161], v[60:61], v[52:53]
	v_cvt_pk_bf16_f32 v130, v154, v155
	v_cvt_pk_bf16_f32 v131, v156, v157
	v_cvt_pk_bf16_f32 v132, v158, v159
	v_cvt_pk_bf16_f32 v133, v160, v161
	global_store_dwordx4 v153, v[130:133], s[4:5]
	v_add_u32_e32 v153, s92, v153
	v_pk_mul_f32 v[154:155], v[46:47], v[38:39]
	v_pk_mul_f32 v[156:157], v[48:49], v[40:41]
	v_pk_mul_f32 v[158:159], v[42:43], v[34:35]
	v_pk_mul_f32 v[160:161], v[44:45], v[36:37]
	v_cvt_pk_bf16_f32 v130, v154, v155
	v_cvt_pk_bf16_f32 v131, v156, v157
	v_cvt_pk_bf16_f32 v132, v158, v159
	v_cvt_pk_bf16_f32 v133, v160, v161
	global_store_dwordx4 v153, v[130:133], s[4:5]
	v_add_u32_e32 v153, s92, v153
	v_pk_mul_f32 v[154:155], v[30:31], v[22:23]
	v_pk_mul_f32 v[156:157], v[32:33], v[24:25]
	v_pk_mul_f32 v[158:159], v[26:27], v[18:19]
	v_pk_mul_f32 v[160:161], v[28:29], v[20:21]
	v_cvt_pk_bf16_f32 v130, v154, v155
	v_cvt_pk_bf16_f32 v131, v156, v157
	v_cvt_pk_bf16_f32 v132, v158, v159
	v_cvt_pk_bf16_f32 v133, v160, v161
	global_store_dwordx4 v153, v[130:133], s[4:5]
	v_add_u32_e32 v153, s92, v153
	v_pk_mul_f32 v[154:155], v[14:15], v[6:7]
	v_pk_mul_f32 v[156:157], v[16:17], v[8:9]
	v_pk_mul_f32 v[158:159], v[10:11], v[2:3]
	v_pk_mul_f32 v[160:161], v[12:13], v[4:5]
	v_cvt_pk_bf16_f32 v130, v154, v155
	v_cvt_pk_bf16_f32 v131, v156, v157
	v_cvt_pk_bf16_f32 v132, v158, v159
	v_cvt_pk_bf16_f32 v133, v160, v161
	global_store_dwordx4 v153, v[130:133], s[4:5]
	s_branch .LBB0_374
